# code placement: 64-byte alignment of the attention loop heads (FoX and differential steady / band loops)
# baseline (speedup 1.0000x reference)
; #define WAIT_BAR(N) asm volatile("s_waitcnt vmcnt(" #N ") lgkmcnt(0)\n\ts_barrier":::"memory")
;   #define DMA_K(t,slot) glds16(ksrc+(long)(t)*KVBLK*PITCH,(unsigned)__builtin_amdgcn_readfirstlane(kdst+(slot)))
;   #define DMA_V(t,slot) glds16(vsrc+(long)(t)*KVBLK*PITCH,(unsigned)__builtin_amdgcn_readfirstlane(vdst+(slot)))
;   #define CMASK(P0,P1,t) do{int jb_=(t)-(NT-4); if(jb_>=0)cmask(P0,P1,jb_,qrel,hi);}while(0)
;   #define BIAS(P0,P1,t) do{ if constexpr(NOBIAS_) {} else if constexpr(MODE==0){ biasf(P0,P1,kbt+(64*(t)+4*hi)); } else { biasd(P0,P1,kb3,qrel-64*((t)-(NT-4))-4*hi); } }while(0)
;   #define START(P0,P1) do{ const float rm=rowmax(P0,P1); resc=false; \
;     { const float dl=rm; mhat=fadd_s(mhat,dl); \
;       _Pragma("unroll") for(int r=0;r<16;++r){P0[r]=fsub_s(P0[r],dl);P1[r]=fsub_s(P1[r],dl);} \
;       } \
;     _Pragma("unroll") for(int r=0;r<16;++r)P0[r]=__builtin_amdgcn_exp2f(P0[r]); }while(0)
;   #define ROT() do{sl_prev=sl_cur;sl_cur=sl_next;sl_next=(sl_next==(NSLOT-1)*SLOTB)?0:sl_next+SLOTB;}while(0)
;   #define CMASK(P0,P1,t) do{}while(0)
;   #define BIAS(P0,P1,t) do{ if constexpr(NOBIAS_) {} else if constexpr(MODE==0){ biasf(P0,P1,kbt+(64*(t)+4*hi)); } }while(0)
;   #define CMASK(P0,P1,t) do{int jb_=(t)-(NT-4); if(jb_>=0)cmask(P0,P1,jb_,qrel,hi);}while(0)
;   #define BIAS(P0,P1,t) do{ if constexpr(NOBIAS_) {} else if constexpr(MODE==0){ biasf(P0,P1,kbt+(64*(t)+4*hi)); } else { biasd(P0,P1,kb3,qrel-64*((t)-(NT-4))-4*hi); } }while(0)
;   #define DMA_K(t,slot) bglds16(rK,kvo,(unsigned)__builtin_amdgcn_readfirstlane((t)*(KVBLK*PITCH*2)),(unsigned)__builtin_amdgcn_readfirstlane(kdst+(slot)))
;   #define CMASK(P0,P1,t) do{}while(0)
; template<int MODE,int THRL> __device__ __forceinline__ void attn_unit(int qb,const bf16*Q,const bf16*__restrict__ K,const bf16*__restrict__ V,bf16*O,const float*__restrict__ cum,const float*__restrict__ relb,const float thr,char*shm,const int wv){
;     ...
;   qkt(pA0,pA1,Kbase,qr,z16,r32,hi);asm volatile("s_nop 15\n\ts_nop 7":"+v"(pA0),"+v"(pA1));BIAS(pA0,pA1,0);CMASK(pA0,pA1,0);
;   START(pA0,pA1);
;   _Pragma("unroll") for(int r=0;r<16;++r)pA1[r]=__builtin_amdgcn_exp2f(pA1[r]);
;   WAIT_BAR(0);
;   DMA_K(3,0);DMA_V(1,SLOTB);
;   ROT();
;   kload8(kf,kp0+sl_cur);
;   WAIT_BAR(2);
;   s16x4 vlo[8],vhi[8]; u32x4 pw0,pw1,pw2,pw3;
;     ...
;   int t=1;
;     ...
;   constexpr int NEAR=(MODE==1)?7:5;
;   for(;t+NEAR<NT;t+=2){
.LBB0_381:
	v_lshlrev_b32_e32 v0, 1, v34
	v_and_b32_e32 v213, 32, v0
	v_lshrrev_b32_e32 v0, 2, v34
	v_and_or_b32 v0, v0, 3, v216
	v_lshlrev_b32_e32 v212, 6, v0
	v_add_u32_e32 v0, 0, v213
	v_add3_u32 v219, v0, v211, v212
	v_max3_f32 v0, v2, v3, v18
	v_max3_f32 v34, v4, v5, v19
	s_waitcnt vmcnt(0) lgkmcnt(0)
	s_barrier
	s_cmp_lg_u32 0, -1
	v_max3_f32 v0, v0, v20, v21
	v_max3_f32 v34, v34, v8, v9
	s_mov_b32 s43, 1
	v_max3_f32 v0, v0, v6, v7
	v_max3_f32 v34, v34, v24, v25
	s_mov_b32 s41, 0
	v_max3_f32 v0, v0, v22, v23
	v_max3_f32 v34, v34, v12, v13
	v_lshl_add_u32 v215, v209, 2, s82
	v_max3_f32 v0, v0, v10, v11
	v_max3_f32 v34, v34, v28, v29
	v_lshl_add_u32 v214, v216, 2, s82
	v_max3_f32 v0, v0, v26, v27
	v_max3_f32 v34, v34, v16, v17
	s_nop 0
	v_max3_f32 v0, v0, v14, v15
	v_max3_f32 v34, v34, v32, v33
	s_nop 0
	v_max3_f32 v0, v0, v30, v31
	s_nop 0
	v_max_f32_e32 v0, v0, v34
	s_nop 0
	v_mov_b32_e32 v34, v0
	s_nop 1
	v_permlane32_swap_b32_e32 v0, v34
	v_max_f32_e32 v0, v0, v34
	s_nop 0
	v_sub_f32_e32 v2, v2, v0
	v_sub_f32_e32 v3, v3, v0
	v_add_f32_e32 v196, v1, v0
	v_sub_f32_e32 v18, v18, v0
	v_sub_f32_e32 v19, v19, v0
	v_sub_f32_e32 v4, v4, v0
	s_nop 0
	v_exp_f32_e32 v64, v2
	v_exp_f32_e32 v65, v3
	v_lshl_add_u64 v[2:3], v[198:199], 0, s[26:27]
	s_mov_b32 s4, m0
	s_mov_b32 m0, s77
	s_nop 0
	global_load_lds_dwordx4 v[2:3], off
	s_mov_b32 m0, s4
	s_cselect_b32 s4, 0, 0
	s_add_i32 s4, s4, s74
	v_lshl_add_u64 v[2:3], v[200:201], 0, s[22:23]
	s_add_i32 s4, s4, 0x8000
	s_mov_b32 s5, m0
	s_mov_b32 m0, s4
	s_nop 0
	global_load_lds_dwordx4 v[2:3], off
	s_mov_b32 m0, s5
	ds_read_b128 v[172:175], v218 offset:8192
	ds_read_b128 v[168:171], v218 offset:8704
	ds_read_b128 v[164:167], v218 offset:10240
	ds_read_b128 v[160:163], v218 offset:10752
	ds_read_b128 v[156:159], v218 offset:12288
	ds_read_b128 v[148:151], v218 offset:12800
	ds_read_b128 v[152:155], v218 offset:14336
	ds_read_b128 v[144:147], v218 offset:14848
	v_sub_f32_e32 v20, v20, v0
	v_sub_f32_e32 v5, v5, v0
	v_sub_f32_e32 v21, v21, v0
	v_sub_f32_e32 v6, v6, v0
	v_sub_f32_e32 v22, v22, v0
	v_sub_f32_e32 v7, v7, v0
	v_sub_f32_e32 v23, v23, v0
	v_sub_f32_e32 v8, v8, v0
	v_sub_f32_e32 v24, v24, v0
	v_sub_f32_e32 v9, v9, v0
	v_sub_f32_e32 v25, v25, v0
	v_sub_f32_e32 v10, v10, v0
	v_sub_f32_e32 v26, v26, v0
	v_sub_f32_e32 v11, v11, v0
	v_sub_f32_e32 v27, v27, v0
	v_sub_f32_e32 v12, v12, v0
	v_sub_f32_e32 v28, v28, v0
	v_sub_f32_e32 v13, v13, v0
	v_sub_f32_e32 v29, v29, v0
	v_sub_f32_e32 v14, v14, v0
	v_sub_f32_e32 v30, v30, v0
	v_sub_f32_e32 v15, v15, v0
	v_sub_f32_e32 v31, v31, v0
	v_sub_f32_e32 v16, v16, v0
	v_sub_f32_e32 v32, v32, v0
	v_sub_f32_e32 v17, v17, v0
	v_sub_f32_e32 v0, v33, v0
	v_exp_f32_e32 v66, v4
	v_exp_f32_e32 v67, v5
	v_exp_f32_e32 v68, v6
	v_exp_f32_e32 v69, v7
	v_exp_f32_e32 v70, v8
	v_exp_f32_e32 v71, v9
	v_exp_f32_e32 v72, v10
	v_exp_f32_e32 v73, v11
	v_exp_f32_e32 v74, v12
	v_exp_f32_e32 v75, v13
	v_exp_f32_e32 v76, v14
	v_exp_f32_e32 v77, v15
	v_exp_f32_e32 v78, v16
	v_exp_f32_e32 v79, v17
	v_exp_f32_e32 v48, v18
	v_exp_f32_e32 v49, v19
	v_exp_f32_e32 v50, v20
	v_exp_f32_e32 v51, v21
	v_exp_f32_e32 v52, v22
	v_exp_f32_e32 v53, v23
	v_exp_f32_e32 v54, v24
	v_exp_f32_e32 v55, v25
	v_exp_f32_e32 v56, v26
	v_exp_f32_e32 v57, v27
	v_exp_f32_e32 v58, v28
	v_exp_f32_e32 v59, v29
	v_exp_f32_e32 v60, v30
	v_exp_f32_e32 v61, v31
	v_exp_f32_e32 v62, v32
	v_exp_f32_e32 v63, v0
	s_waitcnt vmcnt(2) lgkmcnt(0)
	s_barrier
	s_cmp_lt_i32 s21, 7
	v_cmp_gt_u32_e64 s[4:5], 32, v207
	s_cbranch_scc1 .LBB0_397
	v_mov_b32_e32 v14, v1
	v_mov_b32_e32 v15, v1
	s_add_i32 s40, s40, 0x14900
	v_mov_b32_e32 v0, v1
	v_mov_b32_e32 v2, v1
	v_mov_b32_e32 v3, v1
	v_mov_b32_e32 v4, v1
	v_mov_b32_e32 v5, v1
	v_mov_b32_e32 v6, v1
	v_mov_b32_e32 v7, v1
	v_mov_b32_e32 v8, v1
	v_mov_b32_e32 v9, v1
	v_mov_b32_e32 v10, v1
	v_mov_b32_e32 v11, v1
	v_mov_b32_e32 v12, v1
	v_mov_b32_e32 v13, v1
	v_mov_b64_e32 v[46:47], v[14:15]
	v_mov_b64_e32 v[30:31], v[14:15]
	v_lshl_add_u64 v[180:181], v[200:201], 0, s[26:27]
	v_lshl_add_u64 v[182:183], v[198:199], 0, s[28:29]
	v_lshl_add_u32 v184, v210, 4, s40
	s_mov_b32 s56, 0
	s_movk_i32 s41, 0x4000
	s_movk_i32 s43, 0x2000
	v_mov_b32_e32 v220, 0
	s_mov_b32 s42, 6
	v_mov_b64_e32 v[44:45], v[12:13]
	v_mov_b64_e32 v[42:43], v[10:11]
	v_mov_b64_e32 v[40:41], v[8:9]
	v_mov_b64_e32 v[38:39], v[6:7]
	v_mov_b64_e32 v[36:37], v[4:5]
	v_mov_b64_e32 v[34:35], v[2:3]
	v_mov_b64_e32 v[32:33], v[0:1]
	v_mov_b64_e32 v[28:29], v[12:13]
	v_mov_b64_e32 v[26:27], v[10:11]
	v_mov_b64_e32 v[24:25], v[8:9]
	v_mov_b64_e32 v[22:23], v[6:7]
	v_mov_b64_e32 v[20:21], v[4:5]
	v_mov_b64_e32 v[18:19], v[2:3]
	v_mov_b64_e32 v[16:17], v[0:1]
	.p2align 6

; #define WAIT_BAR(N) asm volatile("s_waitcnt vmcnt(" #N ") lgkmcnt(0)\n\ts_barrier":::"memory")
;   #define DMA_K(t,slot) glds16(ksrc+(long)(t)*KVBLK*PITCH,(unsigned)__builtin_amdgcn_readfirstlane(kdst+(slot)))
;   #define DMA_V(t,slot) glds16(vsrc+(long)(t)*KVBLK*PITCH,(unsigned)__builtin_amdgcn_readfirstlane(vdst+(slot)))
;   #define CMASK(P0,P1,t) do{int jb_=(t)-(NT-4); if(jb_>=0)cmask(P0,P1,jb_,qrel,hi);}while(0)
;   #define BIAS(P0,P1,t) do{ if constexpr(NOBIAS_) {} else if constexpr(MODE==0){ biasf(P0,P1,kbt+(64*(t)+4*hi)); } else { biasd(P0,P1,kb3,qrel-64*((t)-(NT-4))-4*hi); } }while(0)
;   #define START(P0,P1) do{ const float rm=rowmax(P0,P1); resc=false; \
;     { const float dl=rm; mhat=fadd_s(mhat,dl); \
;       _Pragma("unroll") for(int r=0;r<16;++r){P0[r]=fsub_s(P0[r],dl);P1[r]=fsub_s(P1[r],dl);} \
;       } \
;     _Pragma("unroll") for(int r=0;r<16;++r)P0[r]=__builtin_amdgcn_exp2f(P0[r]); }while(0)
;   #define ROT() do{sl_prev=sl_cur;sl_cur=sl_next;sl_next=(sl_next==(NSLOT-1)*SLOTB)?0:sl_next+SLOTB;}while(0)
;   #define CMASK(P0,P1,t) do{}while(0)
;   #define BIAS(P0,P1,t) do{ if constexpr(NOBIAS_) {} else if constexpr(MODE==0){ biasf(P0,P1,kbt+(64*(t)+4*hi)); } }while(0)
;   #define CMASK(P0,P1,t) do{int jb_=(t)-(NT-4); if(jb_>=0)cmask(P0,P1,jb_,qrel,hi);}while(0)
;   #define BIAS(P0,P1,t) do{ if constexpr(NOBIAS_) {} else if constexpr(MODE==0){ biasf(P0,P1,kbt+(64*(t)+4*hi)); } else { biasd(P0,P1,kb3,qrel-64*((t)-(NT-4))-4*hi); } }while(0)
;   #define DMA_K(t,slot) bglds16(rK,kvo,(unsigned)__builtin_amdgcn_readfirstlane((t)*(KVBLK*PITCH*2)),(unsigned)__builtin_amdgcn_readfirstlane(kdst+(slot)))
; template<int THRL> __device__ __forceinline__ void attn_unit_d(int qb,const bf16*Q,const bf16*__restrict__ K,const bf16*__restrict__ V,bf16*O,const float*__restrict__ cum,const float*__restrict__ relb,const float thr,char*shm,const int wv){
;     ...
;   DMA_K(2,2*SLOTB);
;   WAIT_BAR(4);
;   qkt(pA0,pA1,Kbase,qr,z16,r32,hi);asm volatile("s_nop 15\n\ts_nop 7":"+v"(pA0),"+v"(pA1));BIAS(pA0,pA1,0);CMASK(pA0,pA1,0);
;   START(pA0,pA1);
;   _Pragma("unroll") for(int r=0;r<16;++r)pA1[r]=__builtin_amdgcn_exp2f(pA1[r]);
;   WAIT_BAR(0);
;   DMA_K(3,0);DMA_V(1,VSLOT);
;   ROT();
;   kload8(kf,kp0+sl_cur);
;   WAIT_BAR(3);
;   s16x4 vlo[8],vhi[8]; u32x4 pw0,pw1,pw2,pw3;
;     ...
;   int t=1;
;     ...
;   constexpr int NEAR=(MODE==1)?7:5;
;   for(;t+NEAR<NT;t+=2){
.LBB0_467:
	v_lshlrev_b32_e32 v34, 1, v0
	v_lshrrev_b32_e32 v0, 2, v0
	s_add_i32 s4, s46, 0x100
	v_and_b32_e32 v244, 32, v34
	v_and_or_b32 v0, v0, 3, v245
	s_lshr_b32 s90, s4, 6
	s_waitcnt vmcnt(0) lgkmcnt(0)
	s_barrier
	v_lshlrev_b32_e32 v242, 6, v0
	v_add_u32_e32 v0, 0, v244
	s_mov_b32 s4, m0
	s_mov_b32 m0, s77
	s_nop 0
	buffer_load_dwordx4 v247, s[12:15], s65 offen lds
	s_mov_b32 m0, s4
	s_cmp_lg_u32 0, -1
	v_add3_u32 v250, v0, v240, v242
	v_max3_f32 v0, v2, v3, v18
	s_cselect_b32 s4, 0, 0
	v_max3_f32 v34, v4, v5, v19
	v_max3_f32 v0, v0, v20, v21
	s_add_i32 s4, s4, s74
	v_max3_f32 v0, v0, v6, v7
	v_max3_f32 v34, v34, v8, v9
	s_add_i32 s5, s4, 0xa000
	s_mov_b32 s6, m0
	s_mov_b32 m0, s5
	s_nop 0
	buffer_load_dwordx4 v248, s[16:19], s64 offen lds
	s_mov_b32 m0, s6
	v_max3_f32 v0, v0, v22, v23
	v_max3_f32 v34, v34, v24, v25
	s_add_i32 s4, s4, 0xc000
	s_mov_b32 s5, m0
	s_mov_b32 m0, s4
	s_nop 0
	buffer_load_dwordx4 v248, s[16:19], s82 offen lds
	s_mov_b32 m0, s5
	v_max3_f32 v0, v0, v10, v11
	v_max3_f32 v34, v34, v12, v13
	ds_read_b128 v[204:207], v249 offset:8192
	ds_read_b128 v[200:203], v249 offset:8704
	ds_read_b128 v[196:199], v249 offset:10240
	ds_read_b128 v[192:195], v249 offset:10752
	ds_read_b128 v[188:191], v249 offset:12288
	ds_read_b128 v[184:187], v249 offset:12800
	ds_read_b128 v[180:183], v249 offset:14336
	ds_read_b128 v[176:179], v249 offset:14848
	v_max3_f32 v0, v0, v26, v27
	v_max3_f32 v34, v34, v28, v29
	s_waitcnt vmcnt(3) lgkmcnt(0)
	s_barrier
	s_mov_b32 s41, 1
	v_max3_f32 v0, v0, v14, v15
	v_max3_f32 v34, v34, v16, v17
	s_mov_b32 s40, 0
	v_max3_f32 v0, v0, v30, v31
	v_max3_f32 v34, v34, v32, v33
	s_movk_i32 s80, 0x4000
	v_max_f32_e32 v0, v0, v34
	s_cmp_lt_u32 s47, 2
	v_mov_b32_e32 v34, v0
	s_nop 1
	v_permlane32_swap_b32_e32 v0, v34
	v_max_f32_e32 v0, v0, v34
	v_cmp_gt_u32_e64 s[4:5], 32, v237
	v_add_f32_e32 v228, v1, v0
	v_sub_f32_e32 v2, v2, v0
	v_sub_f32_e32 v18, v18, v0
	v_sub_f32_e32 v3, v3, v0
	v_sub_f32_e32 v19, v19, v0
	v_sub_f32_e32 v4, v4, v0
	v_sub_f32_e32 v20, v20, v0
	v_sub_f32_e32 v5, v5, v0
	v_sub_f32_e32 v21, v21, v0
	v_sub_f32_e32 v6, v6, v0
	v_sub_f32_e32 v22, v22, v0
	v_sub_f32_e32 v7, v7, v0
	v_sub_f32_e32 v23, v23, v0
	v_sub_f32_e32 v8, v8, v0
	v_sub_f32_e32 v24, v24, v0
	v_sub_f32_e32 v9, v9, v0
	v_sub_f32_e32 v25, v25, v0
	v_sub_f32_e32 v10, v10, v0
	v_sub_f32_e32 v26, v26, v0
	v_sub_f32_e32 v11, v11, v0
	v_sub_f32_e32 v27, v27, v0
	v_sub_f32_e32 v12, v12, v0
	v_sub_f32_e32 v28, v28, v0
	v_sub_f32_e32 v13, v13, v0
	v_sub_f32_e32 v29, v29, v0
	v_sub_f32_e32 v14, v14, v0
	v_sub_f32_e32 v30, v30, v0
	v_sub_f32_e32 v15, v15, v0
	v_sub_f32_e32 v31, v31, v0
	v_sub_f32_e32 v16, v16, v0
	v_sub_f32_e32 v32, v32, v0
	v_sub_f32_e32 v17, v17, v0
	v_sub_f32_e32 v0, v33, v0
	s_nop 0
	v_exp_f32_e32 v96, v2
	v_exp_f32_e32 v97, v3
	v_exp_f32_e32 v98, v4
	v_exp_f32_e32 v99, v5
	v_exp_f32_e32 v100, v6
	v_exp_f32_e32 v101, v7
	v_exp_f32_e32 v102, v8
	v_exp_f32_e32 v103, v9
	v_exp_f32_e32 v104, v10
	v_exp_f32_e32 v105, v11
	v_exp_f32_e32 v106, v12
	v_exp_f32_e32 v107, v13
	v_exp_f32_e32 v108, v14
	v_exp_f32_e32 v109, v15
	v_exp_f32_e32 v110, v16
	v_exp_f32_e32 v111, v17
	v_exp_f32_e32 v80, v18
	v_exp_f32_e32 v81, v19
	v_exp_f32_e32 v82, v20
	v_exp_f32_e32 v83, v21
	v_exp_f32_e32 v84, v22
	v_exp_f32_e32 v85, v23
	v_exp_f32_e32 v86, v24
	v_exp_f32_e32 v87, v25
	v_exp_f32_e32 v88, v26
	v_exp_f32_e32 v89, v27
	v_exp_f32_e32 v90, v28
	v_exp_f32_e32 v91, v29
	v_exp_f32_e32 v92, v30
	v_exp_f32_e32 v93, v31
	v_exp_f32_e32 v94, v32
	v_exp_f32_e32 v95, v0
	v_lshl_add_u32 v243, v238, 2, s56
	v_lshl_add_u32 v241, v245, 2, s56
	s_cbranch_scc1 .LBB0_483
	v_mov_b32_e32 v14, v1
	v_mov_b32_e32 v15, v1
	v_mov_b32_e32 v0, v1
	v_mov_b32_e32 v2, v1
	v_mov_b32_e32 v3, v1
	v_mov_b32_e32 v4, v1
	v_mov_b32_e32 v5, v1
	v_mov_b32_e32 v6, v1
	v_mov_b32_e32 v7, v1
	v_mov_b32_e32 v8, v1
	v_mov_b32_e32 v9, v1
	v_mov_b32_e32 v10, v1
	v_mov_b32_e32 v11, v1
	v_mov_b32_e32 v12, v1
	v_mov_b32_e32 v13, v1
	v_mov_b64_e32 v[78:79], v[14:15]
	v_mov_b64_e32 v[62:63], v[14:15]
	v_mov_b64_e32 v[46:47], v[14:15]
	v_mov_b64_e32 v[30:31], v[14:15]
	s_mov_b32 s6, 0
	s_mov_b32 s42, 1
	s_movk_i32 s48, 0x2000
	v_mov_b32_e32 v251, 0
	s_movk_i32 s43, 0x4000
	v_mov_b64_e32 v[76:77], v[12:13]
	v_mov_b64_e32 v[74:75], v[10:11]
	v_mov_b64_e32 v[72:73], v[8:9]
	v_mov_b64_e32 v[70:71], v[6:7]
	v_mov_b64_e32 v[68:69], v[4:5]
	v_mov_b64_e32 v[66:67], v[2:3]
	v_mov_b64_e32 v[64:65], v[0:1]
	v_mov_b64_e32 v[60:61], v[12:13]
	v_mov_b64_e32 v[58:59], v[10:11]
	v_mov_b64_e32 v[56:57], v[8:9]
	v_mov_b64_e32 v[54:55], v[6:7]
	v_mov_b64_e32 v[52:53], v[4:5]
	v_mov_b64_e32 v[50:51], v[2:3]
	v_mov_b64_e32 v[48:49], v[0:1]
	v_mov_b64_e32 v[44:45], v[12:13]
	v_mov_b64_e32 v[42:43], v[10:11]
	v_mov_b64_e32 v[40:41], v[8:9]
	v_mov_b64_e32 v[38:39], v[6:7]
	v_mov_b64_e32 v[36:37], v[4:5]
	v_mov_b64_e32 v[34:35], v[2:3]
	v_mov_b64_e32 v[32:33], v[0:1]
	v_mov_b64_e32 v[28:29], v[12:13]
	v_mov_b64_e32 v[26:27], v[10:11]
	v_mov_b64_e32 v[24:25], v[8:9]
	v_mov_b64_e32 v[22:23], v[6:7]
	v_mov_b64_e32 v[20:21], v[4:5]
	v_mov_b64_e32 v[18:19], v[2:3]
	v_mov_b64_e32 v[16:17], v[0:1]
	s_movk_i32 s40, 0x4000
	.p2align 6

;   #define RESC() do{ if(resc){ asm volatile("s_waitcnt lgkmcnt(0)":::"memory"); \
;       _Pragma("unroll") for(int d_=0;d_<2;++d_) _Pragma("unroll") for(int r=0;r<16;++r)o[d_][r]*=wsf[crow(r,hi)]; } }while(0)
;   #define ROT() do{sl_prev=sl_cur;sl_cur=sl_next;sl_next=(sl_next==(NSLOT-1)*SLOTB)?0:sl_next+SLOTB;}while(0)
;   #define ENDW(tt) do{ if((tt)+3<NT){WAIT_BAR(2);} else if((tt)+2<NT){WAIT_BAR(1);} else {WAIT_BAR(0);} }while(0)
;   #define RESC() do{ if(resc){ asm volatile("s_waitcnt lgkmcnt(0)":::"memory"); \
;       _Pragma("unroll") for(int d_=0;d_<4;++d_) _Pragma("unroll") for(int r=0;r<16;++r)o[d_][r]*=wsf[crow(r,hi)]; } }while(0)
;   #define ROT() do{sl_prev=sl_cur;sl_cur=sl_next;sl_next=(sl_next==(NSLOT-1)*SLOTB)?0:sl_next+SLOTB;}while(0)
;   #define ENDW(tt) do{ if((tt)+3<NT){WAIT_BAR(3);} else if((tt)+2<NT){WAIT_BAR(2);} else {WAIT_BAR(0);} }while(0)
; template<int THRL> __device__ __forceinline__ void attn_unit_d(int qb,const bf16*Q,const bf16*__restrict__ K,const bf16*__restrict__ V,bf16*O,const float*__restrict__ cum,const float*__restrict__ relb,const float thr,char*shm,const int wv){
;     ...
;   for(;t+1<NT;t+=2){
;     STEP(pB0,pB1,pA0,pA1,t,(t+3<NT),(t+1<NT),(t+1<NT));       ENDW(t);   RESC(); ROT();
;     STEP(pA0,pA1,pB0,pB1,t+1,(t+4<NT),(t+2<NT),(t+2<NT));     ENDW(t+1); RESC(); ROT();
.LBB0_486:
	s_andn2_b64 vcc, exec, s[4:5]
	s_cbranch_vccnz .LBB0_536
	s_lshl_b32 s6, s47, 2
	s_sub_i32 s92, 0, s6
	s_lshl_b32 s6, s41, 6
	v_sub_u32_e32 v2, s10, v245
	s_add_i32 s7, s6, 0x7b
	v_subrev_u32_e32 v252, s6, v2
	v_or_b32_e32 v2, s6, v245
	v_add_u32_e32 v0, s7, v245
	v_sub_u32_e32 v2, s46, v2
	v_cmp_gt_u32_e64 s[4:5], 32, v237
	v_subrev_u32_e32 v0, s46, v0
	v_add_u32_e32 v253, s35, v2
	.p2align 6

; #define WAIT_BAR(N) asm volatile("s_waitcnt vmcnt(" #N ") lgkmcnt(0)\n\ts_barrier":::"memory")
;   #define DMA_K(t,slot) glds16(ksrc+(long)(t)*KVBLK*PITCH,(unsigned)__builtin_amdgcn_readfirstlane(kdst+(slot)))
;   #define DMA_V(t,slot) glds16(vsrc+(long)(t)*KVBLK*PITCH,(unsigned)__builtin_amdgcn_readfirstlane(vdst+(slot)))
;   #define CMASK(P0,P1,t) do{int jb_=(t)-(NT-4); if(jb_>=0)cmask(P0,P1,jb_,qrel,hi);}while(0)
;   #define BIAS(P0,P1,t) do{ if constexpr(NOBIAS_) {} else if constexpr(MODE==0){ biasf(P0,P1,kbt+(64*(t)+4*hi)); } else { biasd(P0,P1,kb3,qrel-64*((t)-(NT-4))-4*hi); } }while(0)
;   #define START(P0,P1) do{ const float rm=rowmax(P0,P1); resc=false; \
;     { const float dl=rm; mhat=fadd_s(mhat,dl); \
;       _Pragma("unroll") for(int r=0;r<16;++r){P0[r]=fsub_s(P0[r],dl);P1[r]=fsub_s(P1[r],dl);} \
;       } \
;     _Pragma("unroll") for(int r=0;r<16;++r)P0[r]=__builtin_amdgcn_exp2f(P0[r]); }while(0)
;   #define ROT() do{sl_prev=sl_cur;sl_cur=sl_next;sl_next=(sl_next==(NSLOT-1)*SLOTB)?0:sl_next+SLOTB;}while(0)
;   #define CMASK(P0,P1,t) do{}while(0)
;   #define BIAS(P0,P1,t) do{ if constexpr(NOBIAS_) {} else if constexpr(MODE==0){ biasf(P0,P1,kbt+(64*(t)+4*hi)); } }while(0)
;   #define CMASK(P0,P1,t) do{int jb_=(t)-(NT-4); if(jb_>=0)cmask(P0,P1,jb_,qrel,hi);}while(0)
;   #define BIAS(P0,P1,t) do{ if constexpr(NOBIAS_) {} else if constexpr(MODE==0){ biasf(P0,P1,kbt+(64*(t)+4*hi)); } else { biasd(P0,P1,kb3,qrel-64*((t)-(NT-4))-4*hi); } }while(0)
;   #define DMA_K(t,slot) bglds16(rK,kvo,(unsigned)__builtin_amdgcn_readfirstlane((t)*(KVBLK*PITCH*2)),(unsigned)__builtin_amdgcn_readfirstlane(kdst+(slot)))
;   #define CMASK(P0,P1,t) do{}while(0)
; template<int MODE,int THRL> __device__ __forceinline__ void attn_unit(int qb,const bf16*Q,const bf16*__restrict__ K,const bf16*__restrict__ V,bf16*O,const float*__restrict__ cum,const float*__restrict__ relb,const float thr,char*shm,const int wv){
;     ...
;   qkt(pA0,pA1,Kbase,qr,z16,r32,hi);asm volatile("s_nop 15\n\ts_nop 7":"+v"(pA0),"+v"(pA1));BIAS(pA0,pA1,0);CMASK(pA0,pA1,0);
;   START(pA0,pA1);
;   _Pragma("unroll") for(int r=0;r<16;++r)pA1[r]=__builtin_amdgcn_exp2f(pA1[r]);
;   WAIT_BAR(0);
;   DMA_K(3,0);DMA_V(1,SLOTB);
;   ROT();
;   kload8(kf,kp0+sl_cur);
;   WAIT_BAR(2);
;   s16x4 vlo[8],vhi[8]; u32x4 pw0,pw1,pw2,pw3;
;     ...
;   int t=1;
;     ...
;   constexpr int NEAR=(MODE==1)?7:5;
;   for(;t+NEAR<NT;t+=2){
.LBB0_1421:
	v_lshlrev_b32_e32 v0, 1, v34
	v_and_b32_e32 v213, 32, v0
	v_lshrrev_b32_e32 v0, 2, v34
	v_and_or_b32 v0, v0, 3, v216
	v_lshlrev_b32_e32 v212, 6, v0
	v_add_u32_e32 v0, 0, v213
	v_add3_u32 v219, v0, v211, v212
	v_max3_f32 v0, v2, v3, v18
	v_max3_f32 v34, v4, v5, v19
	s_waitcnt vmcnt(0) lgkmcnt(0)
	s_barrier
	s_cmp_lg_u32 0, -1
	v_max3_f32 v0, v0, v20, v21
	v_max3_f32 v34, v34, v8, v9
	s_mov_b32 s58, 1
	v_max3_f32 v0, v0, v6, v7
	v_max3_f32 v34, v34, v24, v25
	s_mov_b32 s62, 0
	v_max3_f32 v0, v0, v22, v23
	v_max3_f32 v34, v34, v12, v13
	v_lshl_add_u32 v215, v209, 2, s17
	v_max3_f32 v0, v0, v10, v11
	v_max3_f32 v34, v34, v28, v29
	v_lshl_add_u32 v214, v216, 2, s17
	v_max3_f32 v0, v0, v26, v27
	v_max3_f32 v34, v34, v16, v17
	s_nop 0
	v_max3_f32 v0, v0, v14, v15
	v_max3_f32 v34, v34, v32, v33
	s_nop 0
	v_max3_f32 v0, v0, v30, v31
	s_nop 0
	v_max_f32_e32 v0, v0, v34
	s_nop 0
	v_mov_b32_e32 v34, v0
	s_nop 1
	v_permlane32_swap_b32_e32 v0, v34
	v_max_f32_e32 v0, v0, v34
	s_nop 0
	v_sub_f32_e32 v2, v2, v0
	v_sub_f32_e32 v3, v3, v0
	v_add_f32_e32 v196, v1, v0
	v_sub_f32_e32 v18, v18, v0
	v_sub_f32_e32 v19, v19, v0
	v_sub_f32_e32 v4, v4, v0
	s_nop 0
	v_exp_f32_e32 v64, v2
	v_exp_f32_e32 v65, v3
	v_lshl_add_u64 v[2:3], v[198:199], 0, s[28:29]
	s_mov_b32 s8, m0
	s_mov_b32 m0, s66
	s_nop 0
	global_load_lds_dwordx4 v[2:3], off
	s_mov_b32 m0, s8
	s_cselect_b32 s8, 0, 0
	s_add_i32 s8, s8, s74
	v_lshl_add_u64 v[2:3], v[200:201], 0, s[24:25]
	s_add_i32 s8, s8, 0x8000
	s_mov_b32 s9, m0
	s_mov_b32 m0, s8
	s_nop 0
	global_load_lds_dwordx4 v[2:3], off
	s_mov_b32 m0, s9
	ds_read_b128 v[172:175], v218 offset:8192
	ds_read_b128 v[168:171], v218 offset:8704
	ds_read_b128 v[164:167], v218 offset:10240
	ds_read_b128 v[160:163], v218 offset:10752
	ds_read_b128 v[156:159], v218 offset:12288
	ds_read_b128 v[148:151], v218 offset:12800
	ds_read_b128 v[152:155], v218 offset:14336
	ds_read_b128 v[144:147], v218 offset:14848
	v_sub_f32_e32 v20, v20, v0
	v_sub_f32_e32 v5, v5, v0
	v_sub_f32_e32 v21, v21, v0
	v_sub_f32_e32 v6, v6, v0
	v_sub_f32_e32 v22, v22, v0
	v_sub_f32_e32 v7, v7, v0
	v_sub_f32_e32 v23, v23, v0
	v_sub_f32_e32 v8, v8, v0
	v_sub_f32_e32 v24, v24, v0
	v_sub_f32_e32 v9, v9, v0
	v_sub_f32_e32 v25, v25, v0
	v_sub_f32_e32 v10, v10, v0
	v_sub_f32_e32 v26, v26, v0
	v_sub_f32_e32 v11, v11, v0
	v_sub_f32_e32 v27, v27, v0
	v_sub_f32_e32 v12, v12, v0
	v_sub_f32_e32 v28, v28, v0
	v_sub_f32_e32 v13, v13, v0
	v_sub_f32_e32 v29, v29, v0
	v_sub_f32_e32 v14, v14, v0
	v_sub_f32_e32 v30, v30, v0
	v_sub_f32_e32 v15, v15, v0
	v_sub_f32_e32 v31, v31, v0
	v_sub_f32_e32 v16, v16, v0
	v_sub_f32_e32 v32, v32, v0
	v_sub_f32_e32 v17, v17, v0
	v_sub_f32_e32 v0, v33, v0
	v_exp_f32_e32 v66, v4
	v_exp_f32_e32 v67, v5
	v_exp_f32_e32 v68, v6
	v_exp_f32_e32 v69, v7
	v_exp_f32_e32 v70, v8
	v_exp_f32_e32 v71, v9
	v_exp_f32_e32 v72, v10
	v_exp_f32_e32 v73, v11
	v_exp_f32_e32 v74, v12
	v_exp_f32_e32 v75, v13
	v_exp_f32_e32 v76, v14
	v_exp_f32_e32 v77, v15
	v_exp_f32_e32 v78, v16
	v_exp_f32_e32 v79, v17
	v_exp_f32_e32 v48, v18
	v_exp_f32_e32 v49, v19
	v_exp_f32_e32 v50, v20
	v_exp_f32_e32 v51, v21
	v_exp_f32_e32 v52, v22
	v_exp_f32_e32 v53, v23
	v_exp_f32_e32 v54, v24
	v_exp_f32_e32 v55, v25
	v_exp_f32_e32 v56, v26
	v_exp_f32_e32 v57, v27
	v_exp_f32_e32 v58, v28
	v_exp_f32_e32 v59, v29
	v_exp_f32_e32 v60, v30
	v_exp_f32_e32 v61, v31
	v_exp_f32_e32 v62, v32
	v_exp_f32_e32 v63, v0
	s_waitcnt vmcnt(2) lgkmcnt(0)
	s_barrier
	s_cmp_lt_i32 s23, 7
	v_cmp_gt_u32_e64 s[8:9], 32, v207
	s_cbranch_scc1 .LBB0_1437
	v_mov_b32_e32 v14, v1
	v_mov_b32_e32 v15, v1
	s_add_i32 s54, s54, 0x14900
	v_mov_b32_e32 v0, v1
	v_mov_b32_e32 v2, v1
	v_mov_b32_e32 v3, v1
	v_mov_b32_e32 v4, v1
	v_mov_b32_e32 v5, v1
	v_mov_b32_e32 v6, v1
	v_mov_b32_e32 v7, v1
	v_mov_b32_e32 v8, v1
	v_mov_b32_e32 v9, v1
	v_mov_b32_e32 v10, v1
	v_mov_b32_e32 v11, v1
	v_mov_b32_e32 v12, v1
	v_mov_b32_e32 v13, v1
	v_mov_b64_e32 v[46:47], v[14:15]
	v_mov_b64_e32 v[30:31], v[14:15]
	v_lshl_add_u64 v[180:181], v[200:201], 0, s[28:29]
	v_lshl_add_u64 v[182:183], v[198:199], 0, s[40:41]
	v_lshl_add_u32 v184, v210, 4, s54
	s_mov_b32 s54, 0
	s_movk_i32 s62, 0x4000
	s_movk_i32 s97, 0x2000
	v_mov_b32_e32 v220, 0
	s_mov_b32 s63, 6
	v_mov_b64_e32 v[44:45], v[12:13]
	v_mov_b64_e32 v[42:43], v[10:11]
	v_mov_b64_e32 v[40:41], v[8:9]
	v_mov_b64_e32 v[38:39], v[6:7]
	v_mov_b64_e32 v[36:37], v[4:5]
	v_mov_b64_e32 v[34:35], v[2:3]
	v_mov_b64_e32 v[32:33], v[0:1]
	v_mov_b64_e32 v[28:29], v[12:13]
	v_mov_b64_e32 v[26:27], v[10:11]
	v_mov_b64_e32 v[24:25], v[8:9]
	v_mov_b64_e32 v[22:23], v[6:7]
	v_mov_b64_e32 v[20:21], v[4:5]
	v_mov_b64_e32 v[18:19], v[2:3]
	v_mov_b64_e32 v[16:17], v[0:1]
	.p2align 6

; #define WAIT_BAR(N) asm volatile("s_waitcnt vmcnt(" #N ") lgkmcnt(0)\n\ts_barrier":::"memory")
;   #define DMA_K(t,slot) glds16(ksrc+(long)(t)*KVBLK*PITCH,(unsigned)__builtin_amdgcn_readfirstlane(kdst+(slot)))
;   #define DMA_V(t,slot) glds16(vsrc+(long)(t)*KVBLK*PITCH,(unsigned)__builtin_amdgcn_readfirstlane(vdst+(slot)))
;   #define CMASK(P0,P1,t) do{int jb_=(t)-(NT-4); if(jb_>=0)cmask(P0,P1,jb_,qrel,hi);}while(0)
;   #define BIAS(P0,P1,t) do{ if constexpr(NOBIAS_) {} else if constexpr(MODE==0){ biasf(P0,P1,kbt+(64*(t)+4*hi)); } else { biasd(P0,P1,kb3,qrel-64*((t)-(NT-4))-4*hi); } }while(0)
;   #define START(P0,P1) do{ const float rm=rowmax(P0,P1); resc=false; \
;     { const float dl=rm; mhat=fadd_s(mhat,dl); \
;       _Pragma("unroll") for(int r=0;r<16;++r){P0[r]=fsub_s(P0[r],dl);P1[r]=fsub_s(P1[r],dl);} \
;       } \
;     _Pragma("unroll") for(int r=0;r<16;++r)P0[r]=__builtin_amdgcn_exp2f(P0[r]); }while(0)
;   #define ROT() do{sl_prev=sl_cur;sl_cur=sl_next;sl_next=(sl_next==(NSLOT-1)*SLOTB)?0:sl_next+SLOTB;}while(0)
;   #define CMASK(P0,P1,t) do{}while(0)
;   #define BIAS(P0,P1,t) do{ if constexpr(NOBIAS_) {} else if constexpr(MODE==0){ biasf(P0,P1,kbt+(64*(t)+4*hi)); } }while(0)
;   #define CMASK(P0,P1,t) do{int jb_=(t)-(NT-4); if(jb_>=0)cmask(P0,P1,jb_,qrel,hi);}while(0)
;   #define BIAS(P0,P1,t) do{ if constexpr(NOBIAS_) {} else if constexpr(MODE==0){ biasf(P0,P1,kbt+(64*(t)+4*hi)); } else { biasd(P0,P1,kb3,qrel-64*((t)-(NT-4))-4*hi); } }while(0)
;   #define DMA_K(t,slot) bglds16(rK,kvo,(unsigned)__builtin_amdgcn_readfirstlane((t)*(KVBLK*PITCH*2)),(unsigned)__builtin_amdgcn_readfirstlane(kdst+(slot)))
; template<int THRL> __device__ __forceinline__ void attn_unit_d(int qb,const bf16*Q,const bf16*__restrict__ K,const bf16*__restrict__ V,bf16*O,const float*__restrict__ cum,const float*__restrict__ relb,const float thr,char*shm,const int wv){
;     ...
;   DMA_K(2,2*SLOTB);
;   WAIT_BAR(4);
;   qkt(pA0,pA1,Kbase,qr,z16,r32,hi);asm volatile("s_nop 15\n\ts_nop 7":"+v"(pA0),"+v"(pA1));BIAS(pA0,pA1,0);CMASK(pA0,pA1,0);
;   START(pA0,pA1);
;   _Pragma("unroll") for(int r=0;r<16;++r)pA1[r]=__builtin_amdgcn_exp2f(pA1[r]);
;   WAIT_BAR(0);
;   DMA_K(3,0);DMA_V(1,VSLOT);
;   ROT();
;   kload8(kf,kp0+sl_cur);
;   WAIT_BAR(3);
;   s16x4 vlo[8],vhi[8]; u32x4 pw0,pw1,pw2,pw3;
;     ...
;   int t=1;
;     ...
;   constexpr int NEAR=(MODE==1)?7:5;
;   for(;t+NEAR<NT;t+=2){
.LBB0_1507:
	v_lshlrev_b32_e32 v34, 1, v0
	v_lshrrev_b32_e32 v0, 2, v0
	s_add_i32 s8, s44, 0x100
	v_and_b32_e32 v243, 32, v34
	v_and_or_b32 v0, v0, 3, v244
	s_lshr_b32 s86, s8, 6
	s_waitcnt vmcnt(0) lgkmcnt(0)
	s_barrier
	v_lshlrev_b32_e32 v241, 6, v0
	v_add_u32_e32 v0, 0, v243
	s_mov_b32 s8, m0
	s_mov_b32 m0, s66
	s_nop 0
	buffer_load_dwordx4 v246, s[12:15], s63 offen lds
	s_mov_b32 m0, s8
	s_cmp_lg_u32 0, -1
	v_add3_u32 v249, v0, v239, v241
	v_max3_f32 v0, v2, v3, v18
	s_cselect_b32 s8, 0, 0
	v_max3_f32 v34, v4, v5, v19
	v_max3_f32 v0, v0, v20, v21
	s_add_i32 s8, s8, s74
	v_max3_f32 v0, v0, v6, v7
	v_max3_f32 v34, v34, v8, v9
	s_add_i32 s9, s8, 0xa000
	s_mov_b32 s10, m0
	s_mov_b32 m0, s9
	s_nop 0
	buffer_load_dwordx4 v247, s[16:19], s62 offen lds
	s_mov_b32 m0, s10
	v_max3_f32 v0, v0, v22, v23
	v_max3_f32 v34, v34, v24, v25
	s_add_i32 s8, s8, 0xc000
	s_mov_b32 s9, m0
	s_mov_b32 m0, s8
	s_nop 0
	buffer_load_dwordx4 v247, s[16:19], s76 offen lds
	s_mov_b32 m0, s9
	v_max3_f32 v0, v0, v10, v11
	v_max3_f32 v34, v34, v12, v13
	ds_read_b128 v[204:207], v248 offset:8192
	ds_read_b128 v[200:203], v248 offset:8704
	ds_read_b128 v[196:199], v248 offset:10240
	ds_read_b128 v[192:195], v248 offset:10752
	ds_read_b128 v[188:191], v248 offset:12288
	ds_read_b128 v[184:187], v248 offset:12800
	ds_read_b128 v[180:183], v248 offset:14336
	ds_read_b128 v[176:179], v248 offset:14848
	v_max3_f32 v0, v0, v26, v27
	v_max3_f32 v34, v34, v28, v29
	s_waitcnt vmcnt(3) lgkmcnt(0)
	s_barrier
	s_mov_b32 s48, 1
	v_max3_f32 v0, v0, v14, v15
	v_max3_f32 v34, v34, v16, v17
	s_mov_b32 s46, 0
	v_max3_f32 v0, v0, v30, v31
	v_max3_f32 v34, v34, v32, v33
	s_movk_i32 s88, 0x4000
	v_max_f32_e32 v0, v0, v34
	s_cmp_lt_u32 s45, 2
	v_mov_b32_e32 v34, v0
	s_nop 1
	v_permlane32_swap_b32_e32 v0, v34
	v_max_f32_e32 v0, v0, v34
	v_cmp_gt_u32_e64 s[8:9], 32, v236
	v_add_f32_e32 v228, v1, v0
	v_sub_f32_e32 v2, v2, v0
	v_sub_f32_e32 v18, v18, v0
	v_sub_f32_e32 v3, v3, v0
	v_sub_f32_e32 v19, v19, v0
	v_sub_f32_e32 v4, v4, v0
	v_sub_f32_e32 v20, v20, v0
	v_sub_f32_e32 v5, v5, v0
	v_sub_f32_e32 v21, v21, v0
	v_sub_f32_e32 v6, v6, v0
	v_sub_f32_e32 v22, v22, v0
	v_sub_f32_e32 v7, v7, v0
	v_sub_f32_e32 v23, v23, v0
	v_sub_f32_e32 v8, v8, v0
	v_sub_f32_e32 v24, v24, v0
	v_sub_f32_e32 v9, v9, v0
	v_sub_f32_e32 v25, v25, v0
	v_sub_f32_e32 v10, v10, v0
	v_sub_f32_e32 v26, v26, v0
	v_sub_f32_e32 v11, v11, v0
	v_sub_f32_e32 v27, v27, v0
	v_sub_f32_e32 v12, v12, v0
	v_sub_f32_e32 v28, v28, v0
	v_sub_f32_e32 v13, v13, v0
	v_sub_f32_e32 v29, v29, v0
	v_sub_f32_e32 v14, v14, v0
	v_sub_f32_e32 v30, v30, v0
	v_sub_f32_e32 v15, v15, v0
	v_sub_f32_e32 v31, v31, v0
	v_sub_f32_e32 v16, v16, v0
	v_sub_f32_e32 v32, v32, v0
	v_sub_f32_e32 v17, v17, v0
	v_sub_f32_e32 v0, v33, v0
	s_nop 0
	v_exp_f32_e32 v96, v2
	v_exp_f32_e32 v97, v3
	v_exp_f32_e32 v98, v4
	v_exp_f32_e32 v99, v5
	v_exp_f32_e32 v100, v6
	v_exp_f32_e32 v101, v7
	v_exp_f32_e32 v102, v8
	v_exp_f32_e32 v103, v9
	v_exp_f32_e32 v104, v10
	v_exp_f32_e32 v105, v11
	v_exp_f32_e32 v106, v12
	v_exp_f32_e32 v107, v13
	v_exp_f32_e32 v108, v14
	v_exp_f32_e32 v109, v15
	v_exp_f32_e32 v110, v16
	v_exp_f32_e32 v111, v17
	v_exp_f32_e32 v80, v18
	v_exp_f32_e32 v81, v19
	v_exp_f32_e32 v82, v20
	v_exp_f32_e32 v83, v21
	v_exp_f32_e32 v84, v22
	v_exp_f32_e32 v85, v23
	v_exp_f32_e32 v86, v24
	v_exp_f32_e32 v87, v25
	v_exp_f32_e32 v88, v26
	v_exp_f32_e32 v89, v27
	v_exp_f32_e32 v90, v28
	v_exp_f32_e32 v91, v29
	v_exp_f32_e32 v92, v30
	v_exp_f32_e32 v93, v31
	v_exp_f32_e32 v94, v32
	v_exp_f32_e32 v95, v0
	v_lshl_add_u32 v242, v237, 2, s54
	v_lshl_add_u32 v240, v244, 2, s54
	s_cbranch_scc1 .LBB0_1523
	v_mov_b32_e32 v14, v1
	v_mov_b32_e32 v15, v1
	v_mov_b32_e32 v0, v1
	v_mov_b32_e32 v2, v1
	v_mov_b32_e32 v3, v1
	v_mov_b32_e32 v4, v1
	v_mov_b32_e32 v5, v1
	v_mov_b32_e32 v6, v1
	v_mov_b32_e32 v7, v1
	v_mov_b32_e32 v8, v1
	v_mov_b32_e32 v9, v1
	v_mov_b32_e32 v10, v1
	v_mov_b32_e32 v11, v1
	v_mov_b32_e32 v12, v1
	v_mov_b32_e32 v13, v1
	v_mov_b64_e32 v[78:79], v[14:15]
	v_mov_b64_e32 v[62:63], v[14:15]
	v_mov_b64_e32 v[46:47], v[14:15]
	v_mov_b64_e32 v[30:31], v[14:15]
	s_mov_b32 s10, 0
	s_mov_b32 s47, 1
	s_movk_i32 s89, 0x2000
	v_mov_b32_e32 v250, 0
	s_movk_i32 s49, 0x4000
	v_mov_b64_e32 v[76:77], v[12:13]
	v_mov_b64_e32 v[74:75], v[10:11]
	v_mov_b64_e32 v[72:73], v[8:9]
	v_mov_b64_e32 v[70:71], v[6:7]
	v_mov_b64_e32 v[68:69], v[4:5]
	v_mov_b64_e32 v[66:67], v[2:3]
	v_mov_b64_e32 v[64:65], v[0:1]
	v_mov_b64_e32 v[60:61], v[12:13]
	v_mov_b64_e32 v[58:59], v[10:11]
	v_mov_b64_e32 v[56:57], v[8:9]
	v_mov_b64_e32 v[54:55], v[6:7]
	v_mov_b64_e32 v[52:53], v[4:5]
	v_mov_b64_e32 v[50:51], v[2:3]
	v_mov_b64_e32 v[48:49], v[0:1]
	v_mov_b64_e32 v[44:45], v[12:13]
	v_mov_b64_e32 v[42:43], v[10:11]
	v_mov_b64_e32 v[40:41], v[8:9]
	v_mov_b64_e32 v[38:39], v[6:7]
	v_mov_b64_e32 v[36:37], v[4:5]
	v_mov_b64_e32 v[34:35], v[2:3]
	v_mov_b64_e32 v[32:33], v[0:1]
	v_mov_b64_e32 v[28:29], v[12:13]
	v_mov_b64_e32 v[26:27], v[10:11]
	v_mov_b64_e32 v[24:25], v[8:9]
	v_mov_b64_e32 v[22:23], v[6:7]
	v_mov_b64_e32 v[20:21], v[4:5]
	v_mov_b64_e32 v[18:19], v[2:3]
	v_mov_b64_e32 v[16:17], v[0:1]
	s_movk_i32 s46, 0x4000
	.p2align 6

;   #define RESC() do{ if(resc){ asm volatile("s_waitcnt lgkmcnt(0)":::"memory"); \
;       _Pragma("unroll") for(int d_=0;d_<2;++d_) _Pragma("unroll") for(int r=0;r<16;++r)o[d_][r]*=wsf[crow(r,hi)]; } }while(0)
;   #define ROT() do{sl_prev=sl_cur;sl_cur=sl_next;sl_next=(sl_next==(NSLOT-1)*SLOTB)?0:sl_next+SLOTB;}while(0)
;   #define ENDW(tt) do{ if((tt)+3<NT){WAIT_BAR(2);} else if((tt)+2<NT){WAIT_BAR(1);} else {WAIT_BAR(0);} }while(0)
;   #define RESC() do{ if(resc){ asm volatile("s_waitcnt lgkmcnt(0)":::"memory"); \
;       _Pragma("unroll") for(int d_=0;d_<4;++d_) _Pragma("unroll") for(int r=0;r<16;++r)o[d_][r]*=wsf[crow(r,hi)]; } }while(0)
;   #define ROT() do{sl_prev=sl_cur;sl_cur=sl_next;sl_next=(sl_next==(NSLOT-1)*SLOTB)?0:sl_next+SLOTB;}while(0)
;   #define ENDW(tt) do{ if((tt)+3<NT){WAIT_BAR(3);} else if((tt)+2<NT){WAIT_BAR(2);} else {WAIT_BAR(0);} }while(0)
; template<int THRL> __device__ __forceinline__ void attn_unit_d(int qb,const bf16*Q,const bf16*__restrict__ K,const bf16*__restrict__ V,bf16*O,const float*__restrict__ cum,const float*__restrict__ relb,const float thr,char*shm,const int wv){
;     ...
;   for(;t+1<NT;t+=2){
;     STEP(pB0,pB1,pA0,pA1,t,(t+3<NT),(t+1<NT),(t+1<NT));       ENDW(t);   RESC(); ROT();
;     STEP(pA0,pA1,pB0,pB1,t+1,(t+4<NT),(t+2<NT),(t+2<NT));     ENDW(t+1); RESC(); ROT();
.LBB0_1526:
	s_andn2_b64 vcc, exec, s[8:9]
	s_cbranch_vccnz .LBB0_1576
	s_lshl_b32 s10, s45, 2
	s_sub_i32 s89, 0, s10
	s_lshl_b32 s10, s48, 6
	v_sub_u32_e32 v2, s20, v244
	s_add_i32 s11, s10, 0x7b
	v_subrev_u32_e32 v251, s10, v2
	v_or_b32_e32 v2, s10, v244
	v_add_u32_e32 v0, s11, v244
	v_sub_u32_e32 v2, s44, v2
	v_cmp_gt_u32_e64 s[8:9], 32, v236
	v_subrev_u32_e32 v0, s44, v0
	v_add_u32_e32 v252, s81, v2
	.p2align 6
